# per-unit GEMM loops (P1, up x2, P4): first K-loop iteration peeled with inline-0 srcC on each accumulator's first MFMA; the 128 v_mov zeroing per unit start removed
# speedup vs baseline: 1.0038x; 1.0027x over previous
.LBB0_255:
	s_ashr_i32 s29, s28, 31
	s_lshl_b64 s[30:31], s[28:29], 19
	s_add_u32 s30, s38, s30
	s_addc_u32 s31, s39, s31
	s_and_b64 s[34:35], s[8:9], exec
	s_cselect_b32 s1, s31, s11
	s_cselect_b32 s3, s30, s10
	s_ashr_i32 s27, s26, 31
	s_lshl_b64 s[34:35], s[26:27], 19
	s_add_u32 s34, s40, s34
	s_addc_u32 s35, s41, s35
	s_and_b64 s[36:37], s[8:9], exec
	s_cselect_b32 s27, s35, s13
	s_cselect_b32 s29, s34, s12
	s_add_u32 s10, s10, 0x40080
	s_addc_u32 s11, s11, 0
	s_add_u32 s33, s12, 0x100
	s_addc_u32 s58, s13, 0
	s_mov_b32 s59, -2
	ds_read_b128 v[32:35], v225
	ds_read_b128 v[36:39], v225 offset:1024
	ds_read_b128 v[40:43], v225 offset:2048
	ds_read_b128 v[44:47], v225 offset:3072
	ds_read_b128 v[144:147], v228
	ds_read_b128 v[148:151], v228 offset:1024
	ds_read_b128 v[152:155], v228 offset:2048
	ds_read_b128 v[156:159], v228 offset:3072
	s_add_u32 s12, s10, 0xfffc0080
	s_addc_u32 s13, s11, -1
	s_cmp_eq_u32 s59, 12
	s_cselect_b32 s37, s1, s13
	s_cselect_b32 s36, s3, s12
	s_cselect_b32 s13, s27, s58
	s_cselect_b32 s12, s29, s33
	v_lshl_add_u64 v[216:217], s[10:11], 0, v[206:207]
	s_add_i32 m0, s43, 0xc000
	ds_read_b128 v[160:163], v229
	ds_read_b128 v[164:167], v229 offset:1024
	ds_read_b128 v[168:171], v229 offset:2048
	ds_read_b128 v[172:175], v229 offset:3072
	ds_read_b128 v[176:179], v229 offset:4096
	ds_read_b128 v[180:183], v229 offset:5120
	ds_read_b128 v[184:187], v229 offset:6144
	ds_read_b128 v[188:191], v229 offset:7168
	global_load_lds_dwordx4 v[216:217], off
	v_lshl_add_u64 v[216:217], s[10:11], 0, v[208:209]
	s_add_i32 m0, s43, 0xe000
	s_nop 0
	global_load_lds_dwordx4 v[216:217], off
	s_waitcnt vmcnt(8)
	s_waitcnt lgkmcnt(0)
	s_barrier
	s_setprio 1
	s_waitcnt lgkmcnt(0)
	v_mfma_f32_16x16x32_bf16 v[140:143], v[32:35], v[160:163], 0
	v_mfma_f32_16x16x32_bf16 v[136:139], v[40:43], v[160:163], 0
	v_mfma_f32_16x16x32_bf16 v[124:127], v[32:35], v[168:171], 0
	v_mfma_f32_16x16x32_bf16 v[120:123], v[40:43], v[168:171], 0
	v_mfma_f32_16x16x32_bf16 v[108:111], v[32:35], v[176:179], 0
	v_mfma_f32_16x16x32_bf16 v[104:107], v[40:43], v[176:179], 0
	v_mfma_f32_16x16x32_bf16 v[92:95], v[32:35], v[184:187], 0
	v_mfma_f32_16x16x32_bf16 v[88:91], v[40:43], v[184:187], 0
	v_mfma_f32_16x16x32_bf16 v[140:143], v[36:39], v[164:167], v[140:143]
	v_mfma_f32_16x16x32_bf16 v[136:139], v[44:47], v[164:167], v[136:139]
	v_mfma_f32_16x16x32_bf16 v[124:127], v[36:39], v[172:175], v[124:127]
	v_mfma_f32_16x16x32_bf16 v[120:123], v[44:47], v[172:175], v[120:123]
	v_mfma_f32_16x16x32_bf16 v[108:111], v[36:39], v[180:183], v[108:111]
	v_mfma_f32_16x16x32_bf16 v[104:107], v[44:47], v[180:183], v[104:107]
	v_mfma_f32_16x16x32_bf16 v[92:95], v[36:39], v[188:191], v[92:95]
	v_mfma_f32_16x16x32_bf16 v[88:91], v[44:47], v[188:191], v[88:91]
	s_setprio 0
	s_setprio 1
	v_mfma_f32_16x16x32_bf16 v[132:135], v[144:147], v[160:163], 0
	v_mfma_f32_16x16x32_bf16 v[128:131], v[152:155], v[160:163], 0
	v_mfma_f32_16x16x32_bf16 v[116:119], v[144:147], v[168:171], 0
	v_mfma_f32_16x16x32_bf16 v[112:115], v[152:155], v[168:171], 0
	v_mfma_f32_16x16x32_bf16 v[100:103], v[144:147], v[176:179], 0
	v_mfma_f32_16x16x32_bf16 v[96:99], v[152:155], v[176:179], 0
	v_mfma_f32_16x16x32_bf16 v[84:87], v[144:147], v[184:187], 0
	v_mfma_f32_16x16x32_bf16 v[80:83], v[152:155], v[184:187], 0
	v_mfma_f32_16x16x32_bf16 v[132:135], v[148:151], v[164:167], v[132:135]
	v_mfma_f32_16x16x32_bf16 v[128:131], v[156:159], v[164:167], v[128:131]
	v_mfma_f32_16x16x32_bf16 v[116:119], v[148:151], v[172:175], v[116:119]
	v_mfma_f32_16x16x32_bf16 v[112:115], v[156:159], v[172:175], v[112:115]
	v_mfma_f32_16x16x32_bf16 v[100:103], v[148:151], v[180:183], v[100:103]
	v_mfma_f32_16x16x32_bf16 v[96:99], v[156:159], v[180:183], v[96:99]
	v_mfma_f32_16x16x32_bf16 v[84:87], v[148:151], v[188:191], v[84:87]
	v_mfma_f32_16x16x32_bf16 v[80:83], v[156:159], v[188:191], v[80:83]
	s_setprio 0
	s_barrier
	s_add_i32 s60, s54, s42
	v_lshl_add_u64 v[216:217], s[12:13], 0, v[194:195]
	s_mov_b32 m0, s60
	ds_read_b128 v[160:163], v229 offset:16384
	ds_read_b128 v[164:167], v229 offset:17408
	ds_read_b128 v[168:171], v229 offset:18432
	ds_read_b128 v[172:175], v229 offset:19456
	ds_read_b128 v[176:179], v229 offset:20480
	ds_read_b128 v[180:183], v229 offset:21504
	ds_read_b128 v[184:187], v229 offset:22528
	ds_read_b128 v[188:191], v229 offset:23552
	global_load_lds_dwordx4 v[216:217], off
	s_add_i32 m0, s60, 0x2000
	s_add_u32 s60, s12, 0x40000
	v_lshl_add_u64 v[218:219], s[12:13], 0, v[198:199]
	s_addc_u32 s61, s13, 0
	s_add_i32 s62, s55, s42
	global_load_lds_dwordx4 v[218:219], off
	v_lshl_add_u64 v[220:221], s[60:61], 0, v[194:195]
	s_mov_b32 m0, s62
	v_lshl_add_u64 v[222:223], s[36:37], 0, v[196:197]
	global_load_lds_dwordx4 v[220:221], off
	v_lshl_add_u64 v[220:221], s[60:61], 0, v[198:199]
	s_add_i32 m0, s62, 0x2000
	s_nop 0
	global_load_lds_dwordx4 v[220:221], off
	v_lshl_add_u64 v[220:221], s[36:37], 0, v[192:193]
	s_mov_b32 m0, s43
	s_nop 0
	global_load_lds_dwordx4 v[220:221], off
	s_mov_b32 m0, s44
	s_nop 0
	global_load_lds_dwordx4 v[222:223], off
	s_waitcnt vmcnt(8)
	s_waitcnt lgkmcnt(0)
	s_barrier
	s_setprio 1
	s_waitcnt lgkmcnt(0)
	v_mfma_f32_16x16x32_bf16 v[76:79], v[32:35], v[160:163], 0
	v_mfma_f32_16x16x32_bf16 v[72:75], v[40:43], v[160:163], 0
	v_mfma_f32_16x16x32_bf16 v[60:63], v[32:35], v[168:171], 0
	v_mfma_f32_16x16x32_bf16 v[56:59], v[40:43], v[168:171], 0
	v_mfma_f32_16x16x32_bf16 v[28:31], v[32:35], v[176:179], 0
	v_mfma_f32_16x16x32_bf16 v[24:27], v[40:43], v[176:179], 0
	v_mfma_f32_16x16x32_bf16 v[12:15], v[32:35], v[184:187], 0
	v_mfma_f32_16x16x32_bf16 v[8:11], v[40:43], v[184:187], 0
	v_mfma_f32_16x16x32_bf16 v[76:79], v[36:39], v[164:167], v[76:79]
	v_mfma_f32_16x16x32_bf16 v[72:75], v[44:47], v[164:167], v[72:75]
	v_mfma_f32_16x16x32_bf16 v[60:63], v[36:39], v[172:175], v[60:63]
	v_mfma_f32_16x16x32_bf16 v[56:59], v[44:47], v[172:175], v[56:59]
	v_mfma_f32_16x16x32_bf16 v[28:31], v[36:39], v[180:183], v[28:31]
	v_mfma_f32_16x16x32_bf16 v[24:27], v[44:47], v[180:183], v[24:27]
	v_mfma_f32_16x16x32_bf16 v[12:15], v[36:39], v[188:191], v[12:15]
	v_mfma_f32_16x16x32_bf16 v[8:11], v[44:47], v[188:191], v[8:11]
	s_setprio 0
	s_setprio 1
	v_mfma_f32_16x16x32_bf16 v[20:23], v[144:147], v[176:179], 0
	v_mfma_f32_16x16x32_bf16 v[16:19], v[152:155], v[176:179], 0
	v_mfma_f32_16x16x32_bf16 v[4:7], v[144:147], v[184:187], 0
	v_mfma_f32_16x16x32_bf16 v[0:3], v[152:155], v[184:187], 0
	v_mfma_f32_16x16x32_bf16 v[32:35], v[144:147], v[160:163], 0
	v_mfma_f32_16x16x32_bf16 v[36:39], v[152:155], v[160:163], 0
	v_mfma_f32_16x16x32_bf16 v[40:43], v[144:147], v[168:171], 0
	v_mfma_f32_16x16x32_bf16 v[44:47], v[152:155], v[168:171], 0
	v_mfma_f32_16x16x32_bf16 v[20:23], v[148:151], v[180:183], v[20:23]
	v_mfma_f32_16x16x32_bf16 v[16:19], v[156:159], v[180:183], v[16:19]
	v_mfma_f32_16x16x32_bf16 v[4:7], v[148:151], v[188:191], v[4:7]
	v_mfma_f32_16x16x32_bf16 v[0:3], v[156:159], v[188:191], v[0:3]
	v_mfma_f32_16x16x32_bf16 v[32:35], v[148:151], v[164:167], v[32:35]
	v_mfma_f32_16x16x32_bf16 v[36:39], v[156:159], v[164:167], v[36:39]
	v_mfma_f32_16x16x32_bf16 v[40:43], v[148:151], v[172:175], v[40:43]
	v_mfma_f32_16x16x32_bf16 v[44:47], v[156:159], v[172:175], v[44:47]
	s_setprio 0
	s_barrier
	s_add_i32 s60, 0, 0x18000
	s_add_i32 s61, 0, 0x1c000
	v_add_u32_e32 v68, s60, v224
	v_add_u32_e32 v156, s61, v224
	ds_read_b128 v[48:51], v68
	ds_read_b128 v[52:55], v68 offset:1024
	ds_read_b128 v[64:67], v68 offset:2048
	ds_read_b128 v[68:71], v68 offset:3072
	ds_read_b128 v[144:147], v156
	ds_read_b128 v[148:151], v156 offset:1024
	ds_read_b128 v[152:155], v156 offset:2048
	ds_read_b128 v[156:159], v156 offset:3072
	s_add_u32 s36, s36, 0x40000
	s_addc_u32 s37, s37, 0
	s_mov_b32 m0, s45
	v_lshl_add_u64 v[236:237], s[36:37], 0, v[192:193]
	ds_read_b128 v[160:163], v229 offset:32768
	ds_read_b128 v[164:167], v229 offset:33792
	ds_read_b128 v[168:171], v229 offset:34816
	ds_read_b128 v[172:175], v229 offset:35840
	ds_read_b128 v[176:179], v229 offset:36864
	ds_read_b128 v[180:183], v229 offset:37888
	ds_read_b128 v[184:187], v229 offset:38912
	ds_read_b128 v[188:191], v229 offset:39936
	global_load_lds_dwordx4 v[236:237], off
	v_lshl_add_u64 v[236:237], s[36:37], 0, v[196:197]
	s_mov_b32 m0, s46
	s_nop 0
	global_load_lds_dwordx4 v[236:237], off
	s_waitcnt vmcnt(8)
	s_waitcnt lgkmcnt(0)
	s_barrier
	s_setprio 1
	s_waitcnt lgkmcnt(0)
	v_mfma_f32_16x16x32_bf16 v[140:143], v[48:51], v[160:163], v[140:143]
	v_mfma_f32_16x16x32_bf16 v[136:139], v[64:67], v[160:163], v[136:139]
	v_mfma_f32_16x16x32_bf16 v[124:127], v[48:51], v[168:171], v[124:127]
	v_mfma_f32_16x16x32_bf16 v[120:123], v[64:67], v[168:171], v[120:123]
	v_mfma_f32_16x16x32_bf16 v[108:111], v[48:51], v[176:179], v[108:111]
	v_mfma_f32_16x16x32_bf16 v[104:107], v[64:67], v[176:179], v[104:107]
	v_mfma_f32_16x16x32_bf16 v[92:95], v[48:51], v[184:187], v[92:95]
	v_mfma_f32_16x16x32_bf16 v[88:91], v[64:67], v[184:187], v[88:91]
	v_mfma_f32_16x16x32_bf16 v[140:143], v[52:55], v[164:167], v[140:143]
	v_mfma_f32_16x16x32_bf16 v[136:139], v[68:71], v[164:167], v[136:139]
	v_mfma_f32_16x16x32_bf16 v[124:127], v[52:55], v[172:175], v[124:127]
	v_mfma_f32_16x16x32_bf16 v[120:123], v[68:71], v[172:175], v[120:123]
	v_mfma_f32_16x16x32_bf16 v[108:111], v[52:55], v[180:183], v[108:111]
	v_mfma_f32_16x16x32_bf16 v[104:107], v[68:71], v[180:183], v[104:107]
	v_mfma_f32_16x16x32_bf16 v[92:95], v[52:55], v[188:191], v[92:95]
	v_mfma_f32_16x16x32_bf16 v[88:91], v[68:71], v[188:191], v[88:91]
	s_setprio 0
	s_setprio 1
	v_mfma_f32_16x16x32_bf16 v[132:135], v[144:147], v[160:163], v[132:135]
	v_mfma_f32_16x16x32_bf16 v[128:131], v[152:155], v[160:163], v[128:131]
	v_mfma_f32_16x16x32_bf16 v[116:119], v[144:147], v[168:171], v[116:119]
	v_mfma_f32_16x16x32_bf16 v[112:115], v[152:155], v[168:171], v[112:115]
	v_mfma_f32_16x16x32_bf16 v[100:103], v[144:147], v[176:179], v[100:103]
	v_mfma_f32_16x16x32_bf16 v[96:99], v[152:155], v[176:179], v[96:99]
	v_mfma_f32_16x16x32_bf16 v[84:87], v[144:147], v[184:187], v[84:87]
	v_mfma_f32_16x16x32_bf16 v[80:83], v[152:155], v[184:187], v[80:83]
	v_mfma_f32_16x16x32_bf16 v[132:135], v[148:151], v[164:167], v[132:135]
	v_mfma_f32_16x16x32_bf16 v[128:131], v[156:159], v[164:167], v[128:131]
	v_mfma_f32_16x16x32_bf16 v[116:119], v[148:151], v[172:175], v[116:119]
	v_mfma_f32_16x16x32_bf16 v[112:115], v[156:159], v[172:175], v[112:115]
	v_mfma_f32_16x16x32_bf16 v[100:103], v[148:151], v[180:183], v[100:103]
	v_mfma_f32_16x16x32_bf16 v[96:99], v[156:159], v[180:183], v[96:99]
	v_mfma_f32_16x16x32_bf16 v[84:87], v[148:151], v[188:191], v[84:87]
	v_mfma_f32_16x16x32_bf16 v[80:83], v[156:159], v[188:191], v[80:83]
	s_setprio 0
	s_barrier
	s_add_i32 s36, s60, s42
	v_lshl_add_u64 v[216:217], v[216:217], 0, s[22:23]
	s_mov_b32 m0, s36
	ds_read_b128 v[160:163], v229 offset:49152
	ds_read_b128 v[164:167], v229 offset:50176
	ds_read_b128 v[168:171], v229 offset:51200
	ds_read_b128 v[172:175], v229 offset:52224
	ds_read_b128 v[176:179], v229 offset:53248
	ds_read_b128 v[180:183], v229 offset:54272
	ds_read_b128 v[184:187], v229 offset:55296
	ds_read_b128 v[188:191], v229 offset:56320
	global_load_lds_dwordx4 v[216:217], off
	s_add_i32 m0, s36, 0x2000
	s_add_u32 s12, s12, 0x40080
	v_lshl_add_u64 v[216:217], v[218:219], 0, s[22:23]
	s_addc_u32 s13, s13, 0
	s_add_i32 s36, s61, s42
	global_load_lds_dwordx4 v[216:217], off
	v_lshl_add_u64 v[216:217], s[12:13], 0, v[194:195]
	s_mov_b32 m0, s36
	s_nop 0
	global_load_lds_dwordx4 v[216:217], off
	v_lshl_add_u64 v[216:217], s[12:13], 0, v[198:199]
	s_add_i32 m0, s36, 0x2000
	s_nop 0
	global_load_lds_dwordx4 v[216:217], off
	v_lshl_add_u64 v[216:217], v[220:221], 0, s[22:23]
	s_mov_b32 m0, s49
	s_nop 0
	global_load_lds_dwordx4 v[216:217], off
	v_lshl_add_u64 v[216:217], v[222:223], 0, s[22:23]
	s_mov_b32 m0, s50
	s_nop 0
	global_load_lds_dwordx4 v[216:217], off
	s_waitcnt vmcnt(8)
	s_waitcnt lgkmcnt(0)
	s_barrier
	s_setprio 1
	s_waitcnt lgkmcnt(0)
	v_mfma_f32_16x16x32_bf16 v[76:79], v[48:51], v[160:163], v[76:79]
	v_mfma_f32_16x16x32_bf16 v[72:75], v[64:67], v[160:163], v[72:75]
	v_mfma_f32_16x16x32_bf16 v[60:63], v[48:51], v[168:171], v[60:63]
	v_mfma_f32_16x16x32_bf16 v[56:59], v[64:67], v[168:171], v[56:59]
	v_mfma_f32_16x16x32_bf16 v[28:31], v[48:51], v[176:179], v[28:31]
	v_mfma_f32_16x16x32_bf16 v[24:27], v[64:67], v[176:179], v[24:27]
	v_mfma_f32_16x16x32_bf16 v[12:15], v[48:51], v[184:187], v[12:15]
	v_mfma_f32_16x16x32_bf16 v[8:11], v[64:67], v[184:187], v[8:11]
	v_mfma_f32_16x16x32_bf16 v[76:79], v[52:55], v[164:167], v[76:79]
	v_mfma_f32_16x16x32_bf16 v[72:75], v[68:71], v[164:167], v[72:75]
	v_mfma_f32_16x16x32_bf16 v[60:63], v[52:55], v[172:175], v[60:63]
	v_mfma_f32_16x16x32_bf16 v[56:59], v[68:71], v[172:175], v[56:59]
	v_mfma_f32_16x16x32_bf16 v[28:31], v[52:55], v[180:183], v[28:31]
	v_mfma_f32_16x16x32_bf16 v[24:27], v[68:71], v[180:183], v[24:27]
	v_mfma_f32_16x16x32_bf16 v[12:15], v[52:55], v[188:191], v[12:15]
	v_mfma_f32_16x16x32_bf16 v[8:11], v[68:71], v[188:191], v[8:11]
	s_setprio 0
	s_setprio 1
	v_mfma_f32_16x16x32_bf16 v[32:35], v[144:147], v[160:163], v[32:35]
	v_mfma_f32_16x16x32_bf16 v[68:71], v[148:151], v[164:167], v[32:35]
	v_mfma_f32_16x16x32_bf16 v[32:35], v[152:155], v[160:163], v[36:39]
	v_mfma_f32_16x16x32_bf16 v[64:67], v[156:159], v[164:167], v[32:35]
	v_mfma_f32_16x16x32_bf16 v[32:35], v[144:147], v[168:171], v[40:43]
	v_mfma_f32_16x16x32_bf16 v[52:55], v[148:151], v[172:175], v[32:35]
	v_mfma_f32_16x16x32_bf16 v[32:35], v[152:155], v[168:171], v[44:47]
	v_mfma_f32_16x16x32_bf16 v[20:23], v[144:147], v[176:179], v[20:23]
	v_mfma_f32_16x16x32_bf16 v[16:19], v[152:155], v[176:179], v[16:19]
	v_mfma_f32_16x16x32_bf16 v[4:7], v[144:147], v[184:187], v[4:7]
	v_mfma_f32_16x16x32_bf16 v[0:3], v[152:155], v[184:187], v[0:3]
	v_mfma_f32_16x16x32_bf16 v[48:51], v[156:159], v[172:175], v[32:35]
	v_mfma_f32_16x16x32_bf16 v[20:23], v[148:151], v[180:183], v[20:23]
	v_mfma_f32_16x16x32_bf16 v[16:19], v[156:159], v[180:183], v[16:19]
	v_mfma_f32_16x16x32_bf16 v[4:7], v[148:151], v[188:191], v[4:7]
	v_mfma_f32_16x16x32_bf16 v[0:3], v[156:159], v[188:191], v[0:3]
	s_setprio 0
	s_barrier
	s_add_i32 s59, s59, 2
	s_add_u32 s10, s10, 0x100
	s_addc_u32 s11, s11, 0
	s_add_u32 s33, s33, 0x100
	s_addc_u32 s58, s58, 0
	s_cmp_gt_u32 s59, 13

.LBB0_660:
	s_mov_b32 s63, s62
	s_add_i32 s62, s62, 1
	s_cmp_lt_u32 s63, 3
	s_mov_b64 s[0:1], s[18:19]
	s_cselect_b64 s[6:7], -1, 0
	s_add_i32 s18, s62, s58
	s_mov_b64 s[2:3], s[16:17]
	s_and_b64 s[16:17], s[6:7], exec
	s_mov_b32 s64, s34
	s_cselect_b32 s34, s40, s34
	s_mov_b32 s33, s30
	s_cselect_b32 s30, s18, s30
	s_ashr_i32 s35, s34, 31
	s_lshl_b64 s[16:17], s[34:35], 19
	s_add_u32 s18, s26, s16
	s_addc_u32 s19, s27, s17
	s_and_b64 s[16:17], s[6:7], exec
	s_cselect_b32 s35, s19, s1
	s_cselect_b32 s65, s18, s0
	s_ashr_i32 s31, s30, 31
	s_lshl_b64 s[16:17], s[30:31], 19
	s_add_u32 s16, s49, s16
	s_addc_u32 s17, s50, s17
	s_and_b64 s[6:7], s[6:7], exec
	s_cselect_b32 s31, s17, s3
	s_cselect_b32 s66, s16, s2
	s_add_u32 s0, s0, 0x40080
	s_addc_u32 s1, s1, 0
	s_add_u32 s67, s2, 0x100
	s_addc_u32 s68, s3, 0
	s_mov_b32 s69, -2
	ds_read_b128 v[128:131], v142
	ds_read_b128 v[132:135], v142 offset:1024
	ds_read_b128 v[148:151], v142 offset:2048
	ds_read_b128 v[164:167], v142 offset:3072
	ds_read_b128 v[168:171], v143
	ds_read_b128 v[172:175], v143 offset:1024
	ds_read_b128 v[176:179], v143 offset:2048
	ds_read_b128 v[200:203], v143 offset:3072
	s_add_u32 s2, s0, 0xfffc0080
	s_addc_u32 s3, s1, -1
	s_cmp_eq_u32 s69, 12
	s_cselect_b32 s7, s35, s3
	s_cselect_b32 s6, s65, s2
	s_cselect_b32 s3, s31, s68
	s_cselect_b32 s2, s66, s67
	v_lshl_add_u64 v[136:137], s[0:1], 0, v[160:161]
	s_add_i32 m0, s54, 0xc000
	ds_read_b128 v[206:209], v144
	ds_read_b128 v[210:213], v144 offset:1024
	ds_read_b128 v[214:217], v144 offset:2048
	ds_read_b128 v[218:221], v144 offset:3072
	ds_read_b128 v[222:225], v144 offset:4096
	ds_read_b128 v[232:235], v144 offset:5120
	ds_read_b128 v[236:239], v144 offset:6144
	ds_read_b128 v[240:243], v144 offset:7168
	global_load_lds_dwordx4 v[136:137], off
	v_lshl_add_u64 v[136:137], s[0:1], 0, v[162:163]
	s_add_i32 m0, s54, 0xe000
	s_nop 0
	global_load_lds_dwordx4 v[136:137], off
	s_waitcnt vmcnt(8)
	s_waitcnt lgkmcnt(0)
	s_barrier
	s_setprio 1
	s_waitcnt lgkmcnt(0)
	v_mfma_f32_16x16x32_bf16 v[124:127], v[128:131], v[206:209], 0
	v_mfma_f32_16x16x32_bf16 v[120:123], v[148:151], v[206:209], 0
	v_mfma_f32_16x16x32_bf16 v[108:111], v[128:131], v[214:217], 0
	v_mfma_f32_16x16x32_bf16 v[104:107], v[148:151], v[214:217], 0
	v_mfma_f32_16x16x32_bf16 v[92:95], v[128:131], v[222:225], 0
	v_mfma_f32_16x16x32_bf16 v[88:91], v[148:151], v[222:225], 0
	v_mfma_f32_16x16x32_bf16 v[76:79], v[128:131], v[236:239], 0
	v_mfma_f32_16x16x32_bf16 v[72:75], v[148:151], v[236:239], 0
	v_mfma_f32_16x16x32_bf16 v[124:127], v[132:135], v[210:213], v[124:127]
	v_mfma_f32_16x16x32_bf16 v[120:123], v[164:167], v[210:213], v[120:123]
	v_mfma_f32_16x16x32_bf16 v[108:111], v[132:135], v[218:221], v[108:111]
	v_mfma_f32_16x16x32_bf16 v[104:107], v[164:167], v[218:221], v[104:107]
	v_mfma_f32_16x16x32_bf16 v[92:95], v[132:135], v[232:235], v[92:95]
	v_mfma_f32_16x16x32_bf16 v[88:91], v[164:167], v[232:235], v[88:91]
	v_mfma_f32_16x16x32_bf16 v[76:79], v[132:135], v[240:243], v[76:79]
	v_mfma_f32_16x16x32_bf16 v[72:75], v[164:167], v[240:243], v[72:75]
	s_setprio 0
	s_setprio 1
	v_mfma_f32_16x16x32_bf16 v[116:119], v[168:171], v[206:209], 0
	v_mfma_f32_16x16x32_bf16 v[112:115], v[176:179], v[206:209], 0
	v_mfma_f32_16x16x32_bf16 v[100:103], v[168:171], v[214:217], 0
	v_mfma_f32_16x16x32_bf16 v[96:99], v[176:179], v[214:217], 0
	v_mfma_f32_16x16x32_bf16 v[84:87], v[168:171], v[222:225], 0
	v_mfma_f32_16x16x32_bf16 v[80:83], v[176:179], v[222:225], 0
	v_mfma_f32_16x16x32_bf16 v[68:71], v[168:171], v[236:239], 0
	v_mfma_f32_16x16x32_bf16 v[64:67], v[176:179], v[236:239], 0
	v_mfma_f32_16x16x32_bf16 v[116:119], v[172:175], v[210:213], v[116:119]
	v_mfma_f32_16x16x32_bf16 v[112:115], v[200:203], v[210:213], v[112:115]
	v_mfma_f32_16x16x32_bf16 v[100:103], v[172:175], v[218:221], v[100:103]
	v_mfma_f32_16x16x32_bf16 v[96:99], v[200:203], v[218:221], v[96:99]
	v_mfma_f32_16x16x32_bf16 v[84:87], v[172:175], v[232:235], v[84:87]
	v_mfma_f32_16x16x32_bf16 v[80:83], v[200:203], v[232:235], v[80:83]
	v_mfma_f32_16x16x32_bf16 v[68:71], v[172:175], v[240:243], v[68:71]
	v_mfma_f32_16x16x32_bf16 v[64:67], v[200:203], v[240:243], v[64:67]
	s_setprio 0
	s_barrier
	s_add_i32 s70, s36, s51
	v_lshl_add_u64 v[136:137], s[2:3], 0, v[156:157]
	s_mov_b32 m0, s70
	ds_read_b128 v[206:209], v144 offset:16384
	ds_read_b128 v[210:213], v144 offset:17408
	ds_read_b128 v[214:217], v144 offset:18432
	ds_read_b128 v[218:221], v144 offset:19456
	ds_read_b128 v[222:225], v144 offset:20480
	ds_read_b128 v[232:235], v144 offset:21504
	ds_read_b128 v[236:239], v144 offset:22528
	ds_read_b128 v[240:243], v144 offset:23552
	global_load_lds_dwordx4 v[136:137], off
	s_add_i32 m0, s70, 0x2000
	s_add_u32 s70, s2, 0x40000
	v_lshl_add_u64 v[180:181], s[2:3], 0, v[152:153]
	s_addc_u32 s71, s3, 0
	s_add_i32 s72, s37, s51
	global_load_lds_dwordx4 v[180:181], off
	v_lshl_add_u64 v[244:245], s[70:71], 0, v[156:157]
	s_mov_b32 m0, s72
	v_lshl_add_u64 v[246:247], s[6:7], 0, v[154:155]
	global_load_lds_dwordx4 v[244:245], off
	v_lshl_add_u64 v[244:245], s[70:71], 0, v[152:153]
	s_add_i32 m0, s72, 0x2000
	s_nop 0
	global_load_lds_dwordx4 v[244:245], off
	v_lshl_add_u64 v[244:245], s[6:7], 0, v[158:159]
	s_mov_b32 m0, s54
	s_nop 0
	global_load_lds_dwordx4 v[244:245], off
	s_mov_b32 m0, s55
	s_nop 0
	global_load_lds_dwordx4 v[246:247], off
	s_waitcnt vmcnt(8)
	s_waitcnt lgkmcnt(0)
	s_barrier
	s_setprio 1
	s_waitcnt lgkmcnt(0)
	v_mfma_f32_16x16x32_bf16 v[60:63], v[128:131], v[206:209], 0
	v_mfma_f32_16x16x32_bf16 v[56:59], v[148:151], v[206:209], 0
	v_mfma_f32_16x16x32_bf16 v[44:47], v[128:131], v[214:217], 0
	v_mfma_f32_16x16x32_bf16 v[40:43], v[148:151], v[214:217], 0
	v_mfma_f32_16x16x32_bf16 v[28:31], v[128:131], v[222:225], 0
	v_mfma_f32_16x16x32_bf16 v[24:27], v[148:151], v[222:225], 0
	v_mfma_f32_16x16x32_bf16 v[12:15], v[128:131], v[236:239], 0
	v_mfma_f32_16x16x32_bf16 v[8:11], v[148:151], v[236:239], 0
	v_mfma_f32_16x16x32_bf16 v[60:63], v[132:135], v[210:213], v[60:63]
	v_mfma_f32_16x16x32_bf16 v[56:59], v[164:167], v[210:213], v[56:59]
	v_mfma_f32_16x16x32_bf16 v[44:47], v[132:135], v[218:221], v[44:47]
	v_mfma_f32_16x16x32_bf16 v[40:43], v[164:167], v[218:221], v[40:43]
	v_mfma_f32_16x16x32_bf16 v[28:31], v[132:135], v[232:235], v[28:31]
	v_mfma_f32_16x16x32_bf16 v[24:27], v[164:167], v[232:235], v[24:27]
	v_mfma_f32_16x16x32_bf16 v[12:15], v[132:135], v[240:243], v[12:15]
	v_mfma_f32_16x16x32_bf16 v[8:11], v[164:167], v[240:243], v[8:11]
	s_setprio 0
	s_setprio 1
	v_mfma_f32_16x16x32_bf16 v[52:55], v[168:171], v[206:209], 0
	v_mfma_f32_16x16x32_bf16 v[48:51], v[176:179], v[206:209], 0
	v_mfma_f32_16x16x32_bf16 v[36:39], v[168:171], v[214:217], 0
	v_mfma_f32_16x16x32_bf16 v[32:35], v[176:179], v[214:217], 0
	v_mfma_f32_16x16x32_bf16 v[20:23], v[168:171], v[222:225], 0
	v_mfma_f32_16x16x32_bf16 v[16:19], v[176:179], v[222:225], 0
	v_mfma_f32_16x16x32_bf16 v[4:7], v[168:171], v[236:239], 0
	v_mfma_f32_16x16x32_bf16 v[0:3], v[176:179], v[236:239], 0
	v_mfma_f32_16x16x32_bf16 v[52:55], v[172:175], v[210:213], v[52:55]
	v_mfma_f32_16x16x32_bf16 v[48:51], v[200:203], v[210:213], v[48:51]
	v_mfma_f32_16x16x32_bf16 v[36:39], v[172:175], v[218:221], v[36:39]
	v_mfma_f32_16x16x32_bf16 v[32:35], v[200:203], v[218:221], v[32:35]
	v_mfma_f32_16x16x32_bf16 v[20:23], v[172:175], v[232:235], v[20:23]
	v_mfma_f32_16x16x32_bf16 v[16:19], v[200:203], v[232:235], v[16:19]
	v_mfma_f32_16x16x32_bf16 v[4:7], v[172:175], v[240:243], v[4:7]
	v_mfma_f32_16x16x32_bf16 v[0:3], v[200:203], v[240:243], v[0:3]
	s_setprio 0
	s_barrier
	v_add_u32_e32 v147, s45, v140
	ds_read_b128 v[128:131], v147
	ds_read_b128 v[132:135], v147 offset:1024
	ds_read_b128 v[148:151], v147 offset:2048
	ds_read_b128 v[164:167], v147 offset:3072
	v_add_u32_e32 v147, s46, v140
	ds_read_b128 v[168:171], v147
	ds_read_b128 v[172:175], v147 offset:1024
	ds_read_b128 v[176:179], v147 offset:2048
	ds_read_b128 v[200:203], v147 offset:3072
	s_add_u32 s6, s6, 0x40000
	s_addc_u32 s7, s7, 0
	s_mov_b32 m0, s56
	v_lshl_add_u64 v[248:249], s[6:7], 0, v[158:159]
	ds_read_b128 v[206:209], v144 offset:32768
	ds_read_b128 v[210:213], v144 offset:33792
	ds_read_b128 v[214:217], v144 offset:34816
	ds_read_b128 v[218:221], v144 offset:35840
	ds_read_b128 v[222:225], v144 offset:36864
	ds_read_b128 v[232:235], v144 offset:37888
	ds_read_b128 v[236:239], v144 offset:38912
	ds_read_b128 v[240:243], v144 offset:39936
	global_load_lds_dwordx4 v[248:249], off
	v_lshl_add_u64 v[248:249], s[6:7], 0, v[154:155]
	s_mov_b32 m0, s57
	s_nop 0
	global_load_lds_dwordx4 v[248:249], off
	s_waitcnt vmcnt(8)
	s_waitcnt lgkmcnt(0)
	s_barrier
	s_setprio 1
	s_waitcnt lgkmcnt(0)
	v_mfma_f32_16x16x32_bf16 v[124:127], v[128:131], v[206:209], v[124:127]
	v_mfma_f32_16x16x32_bf16 v[120:123], v[148:151], v[206:209], v[120:123]
	v_mfma_f32_16x16x32_bf16 v[108:111], v[128:131], v[214:217], v[108:111]
	v_mfma_f32_16x16x32_bf16 v[104:107], v[148:151], v[214:217], v[104:107]
	v_mfma_f32_16x16x32_bf16 v[92:95], v[128:131], v[222:225], v[92:95]
	v_mfma_f32_16x16x32_bf16 v[88:91], v[148:151], v[222:225], v[88:91]
	v_mfma_f32_16x16x32_bf16 v[76:79], v[128:131], v[236:239], v[76:79]
	v_mfma_f32_16x16x32_bf16 v[72:75], v[148:151], v[236:239], v[72:75]
	v_mfma_f32_16x16x32_bf16 v[124:127], v[132:135], v[210:213], v[124:127]
	v_mfma_f32_16x16x32_bf16 v[120:123], v[164:167], v[210:213], v[120:123]
	v_mfma_f32_16x16x32_bf16 v[108:111], v[132:135], v[218:221], v[108:111]
	v_mfma_f32_16x16x32_bf16 v[104:107], v[164:167], v[218:221], v[104:107]
	v_mfma_f32_16x16x32_bf16 v[92:95], v[132:135], v[232:235], v[92:95]
	v_mfma_f32_16x16x32_bf16 v[88:91], v[164:167], v[232:235], v[88:91]
	v_mfma_f32_16x16x32_bf16 v[76:79], v[132:135], v[240:243], v[76:79]
	v_mfma_f32_16x16x32_bf16 v[72:75], v[164:167], v[240:243], v[72:75]
	s_setprio 0
	s_setprio 1
	v_mfma_f32_16x16x32_bf16 v[116:119], v[168:171], v[206:209], v[116:119]
	v_mfma_f32_16x16x32_bf16 v[112:115], v[176:179], v[206:209], v[112:115]
	v_mfma_f32_16x16x32_bf16 v[100:103], v[168:171], v[214:217], v[100:103]
	v_mfma_f32_16x16x32_bf16 v[96:99], v[176:179], v[214:217], v[96:99]
	v_mfma_f32_16x16x32_bf16 v[84:87], v[168:171], v[222:225], v[84:87]
	v_mfma_f32_16x16x32_bf16 v[80:83], v[176:179], v[222:225], v[80:83]
	v_mfma_f32_16x16x32_bf16 v[68:71], v[168:171], v[236:239], v[68:71]
	v_mfma_f32_16x16x32_bf16 v[64:67], v[176:179], v[236:239], v[64:67]
	v_mfma_f32_16x16x32_bf16 v[116:119], v[172:175], v[210:213], v[116:119]
	v_mfma_f32_16x16x32_bf16 v[112:115], v[200:203], v[210:213], v[112:115]
	v_mfma_f32_16x16x32_bf16 v[100:103], v[172:175], v[218:221], v[100:103]
	v_mfma_f32_16x16x32_bf16 v[96:99], v[200:203], v[218:221], v[96:99]
	v_mfma_f32_16x16x32_bf16 v[84:87], v[172:175], v[232:235], v[84:87]
	v_mfma_f32_16x16x32_bf16 v[80:83], v[200:203], v[232:235], v[80:83]
	v_mfma_f32_16x16x32_bf16 v[68:71], v[172:175], v[240:243], v[68:71]
	v_mfma_f32_16x16x32_bf16 v[64:67], v[200:203], v[240:243], v[64:67]
	s_setprio 0
	s_barrier
	s_add_i32 s6, s45, s51
	v_lshl_add_u64 v[136:137], v[136:137], 0, s[22:23]
	s_mov_b32 m0, s6
	ds_read_b128 v[206:209], v144 offset:49152
	ds_read_b128 v[210:213], v144 offset:50176
	ds_read_b128 v[214:217], v144 offset:51200
	ds_read_b128 v[218:221], v144 offset:52224
	ds_read_b128 v[222:225], v144 offset:53248
	ds_read_b128 v[232:235], v144 offset:54272
	ds_read_b128 v[236:239], v144 offset:55296
	ds_read_b128 v[240:243], v144 offset:56320
	global_load_lds_dwordx4 v[136:137], off
	s_add_i32 m0, s6, 0x2000
	s_add_u32 s2, s2, 0x40080
	v_lshl_add_u64 v[136:137], v[180:181], 0, s[22:23]
	s_addc_u32 s3, s3, 0
	s_add_i32 s6, s46, s51
	global_load_lds_dwordx4 v[136:137], off
	v_lshl_add_u64 v[136:137], s[2:3], 0, v[156:157]
	s_mov_b32 m0, s6
	s_nop 0
	global_load_lds_dwordx4 v[136:137], off
	v_lshl_add_u64 v[136:137], s[2:3], 0, v[152:153]
	s_add_i32 m0, s6, 0x2000
	s_nop 0
	global_load_lds_dwordx4 v[136:137], off
	v_lshl_add_u64 v[136:137], v[244:245], 0, s[22:23]
	s_mov_b32 m0, s59
	s_nop 0
	global_load_lds_dwordx4 v[136:137], off
	v_lshl_add_u64 v[136:137], v[246:247], 0, s[22:23]
	s_mov_b32 m0, s60
	s_nop 0
	global_load_lds_dwordx4 v[136:137], off
	s_waitcnt vmcnt(8)
	s_waitcnt lgkmcnt(0)
	s_barrier
	s_setprio 1
	s_waitcnt lgkmcnt(0)
	v_mfma_f32_16x16x32_bf16 v[60:63], v[128:131], v[206:209], v[60:63]
	v_mfma_f32_16x16x32_bf16 v[56:59], v[148:151], v[206:209], v[56:59]
	v_mfma_f32_16x16x32_bf16 v[44:47], v[128:131], v[214:217], v[44:47]
	v_mfma_f32_16x16x32_bf16 v[40:43], v[148:151], v[214:217], v[40:43]
	v_mfma_f32_16x16x32_bf16 v[28:31], v[128:131], v[222:225], v[28:31]
	v_mfma_f32_16x16x32_bf16 v[24:27], v[148:151], v[222:225], v[24:27]
	v_mfma_f32_16x16x32_bf16 v[12:15], v[128:131], v[236:239], v[12:15]
	v_mfma_f32_16x16x32_bf16 v[8:11], v[148:151], v[236:239], v[8:11]
	v_mfma_f32_16x16x32_bf16 v[60:63], v[132:135], v[210:213], v[60:63]
	v_mfma_f32_16x16x32_bf16 v[56:59], v[164:167], v[210:213], v[56:59]
	v_mfma_f32_16x16x32_bf16 v[44:47], v[132:135], v[218:221], v[44:47]
	v_mfma_f32_16x16x32_bf16 v[40:43], v[164:167], v[218:221], v[40:43]
	v_mfma_f32_16x16x32_bf16 v[28:31], v[132:135], v[232:235], v[28:31]
	v_mfma_f32_16x16x32_bf16 v[24:27], v[164:167], v[232:235], v[24:27]
	v_mfma_f32_16x16x32_bf16 v[12:15], v[132:135], v[240:243], v[12:15]
	v_mfma_f32_16x16x32_bf16 v[8:11], v[164:167], v[240:243], v[8:11]
	s_setprio 0
	s_setprio 1
	v_mfma_f32_16x16x32_bf16 v[52:55], v[168:171], v[206:209], v[52:55]
	v_mfma_f32_16x16x32_bf16 v[48:51], v[176:179], v[206:209], v[48:51]
	v_mfma_f32_16x16x32_bf16 v[36:39], v[168:171], v[214:217], v[36:39]
	v_mfma_f32_16x16x32_bf16 v[32:35], v[176:179], v[214:217], v[32:35]
	v_mfma_f32_16x16x32_bf16 v[20:23], v[168:171], v[222:225], v[20:23]
	v_mfma_f32_16x16x32_bf16 v[16:19], v[176:179], v[222:225], v[16:19]
	v_mfma_f32_16x16x32_bf16 v[4:7], v[168:171], v[236:239], v[4:7]
	v_mfma_f32_16x16x32_bf16 v[0:3], v[176:179], v[236:239], v[0:3]
	v_mfma_f32_16x16x32_bf16 v[52:55], v[172:175], v[210:213], v[52:55]
	v_mfma_f32_16x16x32_bf16 v[48:51], v[200:203], v[210:213], v[48:51]
	v_mfma_f32_16x16x32_bf16 v[36:39], v[172:175], v[218:221], v[36:39]
	v_mfma_f32_16x16x32_bf16 v[32:35], v[200:203], v[218:221], v[32:35]
	v_mfma_f32_16x16x32_bf16 v[20:23], v[172:175], v[232:235], v[20:23]
	v_mfma_f32_16x16x32_bf16 v[16:19], v[200:203], v[232:235], v[16:19]
	v_mfma_f32_16x16x32_bf16 v[4:7], v[172:175], v[240:243], v[4:7]
	v_mfma_f32_16x16x32_bf16 v[0:3], v[200:203], v[240:243], v[0:3]
	s_setprio 0
	s_barrier
	s_add_i32 s69, s69, 2
	s_add_u32 s0, s0, 0x100
	s_addc_u32 s1, s1, 0
	s_add_u32 s67, s67, 0x100
	s_addc_u32 s68, s68, 0
	s_cmp_gt_u32 s69, 13

.LBB0_767:
	s_ashr_i32 s31, s30, 31
	s_lshl_b64 s[34:35], s[30:31], 19
	s_add_u32 s34, s41, s34
	s_addc_u32 s35, s46, s35
	s_and_b64 s[36:37], s[8:9], exec
	s_cselect_b32 s1, s35, s11
	s_cselect_b32 s3, s34, s10
	s_ashr_i32 s29, s28, 31
	s_lshl_b64 s[36:37], s[28:29], 19
	s_add_u32 s36, s47, s36
	s_addc_u32 s37, s48, s37
	s_and_b64 s[44:45], s[8:9], exec
	s_cselect_b32 s29, s37, s13
	s_cselect_b32 s31, s36, s12
	s_add_u32 s10, s10, 0x40080
	s_addc_u32 s11, s11, 0
	s_add_u32 s33, s12, 0x100
	s_addc_u32 s67, s13, 0
	s_mov_b32 s68, -2
	ds_read_b128 v[32:35], v232
	ds_read_b128 v[36:39], v232 offset:1024
	ds_read_b128 v[40:43], v232 offset:2048
	ds_read_b128 v[44:47], v232 offset:3072
	ds_read_b128 v[48:51], v233
	ds_read_b128 v[56:59], v233 offset:1024
	ds_read_b128 v[64:67], v233 offset:2048
	ds_read_b128 v[68:71], v233 offset:3072
	s_add_u32 s12, s10, 0xfffc0080
	s_addc_u32 s13, s11, -1
	s_cmp_eq_u32 s68, 12
	s_cselect_b32 s45, s1, s13
	s_cselect_b32 s44, s3, s12
	s_cselect_b32 s13, s29, s67
	s_cselect_b32 s12, s31, s33
	v_lshl_add_u64 v[218:219], s[10:11], 0, v[208:209]
	s_add_i32 m0, s50, 0xc000
	ds_read_b128 v[160:163], v234
	ds_read_b128 v[164:167], v234 offset:1024
	ds_read_b128 v[168:171], v234 offset:2048
	ds_read_b128 v[172:175], v234 offset:3072
	ds_read_b128 v[176:179], v234 offset:4096
	ds_read_b128 v[180:183], v234 offset:5120
	ds_read_b128 v[184:187], v234 offset:6144
	ds_read_b128 v[188:191], v234 offset:7168
	global_load_lds_dwordx4 v[218:219], off
	v_lshl_add_u64 v[218:219], s[10:11], 0, v[210:211]
	s_add_i32 m0, s50, 0xe000
	s_nop 0
	global_load_lds_dwordx4 v[218:219], off
	s_waitcnt vmcnt(8)
	s_waitcnt lgkmcnt(0)
	s_barrier
	s_setprio 1
	s_waitcnt lgkmcnt(0)
	v_mfma_f32_16x16x32_bf16 v[156:159], v[32:35], v[160:163], 0
	v_mfma_f32_16x16x32_bf16 v[152:155], v[40:43], v[160:163], 0
	v_mfma_f32_16x16x32_bf16 v[140:143], v[32:35], v[168:171], 0
	v_mfma_f32_16x16x32_bf16 v[136:139], v[40:43], v[168:171], 0
	v_mfma_f32_16x16x32_bf16 v[124:127], v[32:35], v[176:179], 0
	v_mfma_f32_16x16x32_bf16 v[120:123], v[40:43], v[176:179], 0
	v_mfma_f32_16x16x32_bf16 v[108:111], v[32:35], v[184:187], 0
	v_mfma_f32_16x16x32_bf16 v[104:107], v[40:43], v[184:187], 0
	v_mfma_f32_16x16x32_bf16 v[156:159], v[36:39], v[164:167], v[156:159]
	v_mfma_f32_16x16x32_bf16 v[152:155], v[44:47], v[164:167], v[152:155]
	v_mfma_f32_16x16x32_bf16 v[140:143], v[36:39], v[172:175], v[140:143]
	v_mfma_f32_16x16x32_bf16 v[136:139], v[44:47], v[172:175], v[136:139]
	v_mfma_f32_16x16x32_bf16 v[124:127], v[36:39], v[180:183], v[124:127]
	v_mfma_f32_16x16x32_bf16 v[120:123], v[44:47], v[180:183], v[120:123]
	v_mfma_f32_16x16x32_bf16 v[108:111], v[36:39], v[188:191], v[108:111]
	v_mfma_f32_16x16x32_bf16 v[104:107], v[44:47], v[188:191], v[104:107]
	s_setprio 0
	s_setprio 1
	v_mfma_f32_16x16x32_bf16 v[148:151], v[48:51], v[160:163], 0
	v_mfma_f32_16x16x32_bf16 v[144:147], v[64:67], v[160:163], 0
	v_mfma_f32_16x16x32_bf16 v[132:135], v[48:51], v[168:171], 0
	v_mfma_f32_16x16x32_bf16 v[128:131], v[64:67], v[168:171], 0
	v_mfma_f32_16x16x32_bf16 v[116:119], v[48:51], v[176:179], 0
	v_mfma_f32_16x16x32_bf16 v[112:115], v[64:67], v[176:179], 0
	v_mfma_f32_16x16x32_bf16 v[100:103], v[48:51], v[184:187], 0
	v_mfma_f32_16x16x32_bf16 v[96:99], v[64:67], v[184:187], 0
	v_mfma_f32_16x16x32_bf16 v[148:151], v[56:59], v[164:167], v[148:151]
	v_mfma_f32_16x16x32_bf16 v[144:147], v[68:71], v[164:167], v[144:147]
	v_mfma_f32_16x16x32_bf16 v[132:135], v[56:59], v[172:175], v[132:135]
	v_mfma_f32_16x16x32_bf16 v[128:131], v[68:71], v[172:175], v[128:131]
	v_mfma_f32_16x16x32_bf16 v[116:119], v[56:59], v[180:183], v[116:119]
	v_mfma_f32_16x16x32_bf16 v[112:115], v[68:71], v[180:183], v[112:115]
	v_mfma_f32_16x16x32_bf16 v[100:103], v[56:59], v[188:191], v[100:103]
	v_mfma_f32_16x16x32_bf16 v[96:99], v[68:71], v[188:191], v[96:99]
	s_setprio 0
	s_barrier
	s_add_i32 s69, s63, s49
	v_lshl_add_u64 v[222:223], s[12:13], 0, v[196:197]
	s_mov_b32 m0, s69
	ds_read_b128 v[160:163], v234 offset:16384
	ds_read_b128 v[164:167], v234 offset:17408
	ds_read_b128 v[168:171], v234 offset:18432
	ds_read_b128 v[172:175], v234 offset:19456
	ds_read_b128 v[176:179], v234 offset:20480
	ds_read_b128 v[180:183], v234 offset:21504
	ds_read_b128 v[184:187], v234 offset:22528
	ds_read_b128 v[188:191], v234 offset:23552
	global_load_lds_dwordx4 v[222:223], off
	s_add_i32 m0, s69, 0x2000
	s_add_u32 s70, s12, 0x40000
	v_lshl_add_u64 v[224:225], s[12:13], 0, v[200:201]
	s_addc_u32 s71, s13, 0
	s_add_i32 s69, s64, s49
	global_load_lds_dwordx4 v[224:225], off
	v_lshl_add_u64 v[218:219], s[70:71], 0, v[196:197]
	s_mov_b32 m0, s69
	v_lshl_add_u64 v[240:241], s[44:45], 0, v[194:195]
	global_load_lds_dwordx4 v[218:219], off
	v_lshl_add_u64 v[218:219], s[70:71], 0, v[200:201]
	s_add_i32 m0, s69, 0x2000
	v_lshl_add_u64 v[242:243], s[44:45], 0, v[198:199]
	global_load_lds_dwordx4 v[218:219], off
	s_mov_b32 m0, s50
	s_nop 0
	global_load_lds_dwordx4 v[240:241], off
	s_mov_b32 m0, s51
	s_nop 0
	global_load_lds_dwordx4 v[242:243], off
	s_waitcnt vmcnt(8)
	s_waitcnt lgkmcnt(0)
	s_barrier
	s_setprio 1
	s_waitcnt lgkmcnt(0)
	v_mfma_f32_16x16x32_bf16 v[92:95], v[32:35], v[160:163], 0
	v_mfma_f32_16x16x32_bf16 v[88:91], v[40:43], v[160:163], 0
	v_mfma_f32_16x16x32_bf16 v[76:79], v[32:35], v[168:171], 0
	v_mfma_f32_16x16x32_bf16 v[72:75], v[40:43], v[168:171], 0
	v_mfma_f32_16x16x32_bf16 v[28:31], v[32:35], v[176:179], 0
	v_mfma_f32_16x16x32_bf16 v[24:27], v[40:43], v[176:179], 0
	v_mfma_f32_16x16x32_bf16 v[12:15], v[32:35], v[184:187], 0
	v_mfma_f32_16x16x32_bf16 v[8:11], v[40:43], v[184:187], 0
	v_mfma_f32_16x16x32_bf16 v[92:95], v[36:39], v[164:167], v[92:95]
	v_mfma_f32_16x16x32_bf16 v[88:91], v[44:47], v[164:167], v[88:91]
	v_mfma_f32_16x16x32_bf16 v[76:79], v[36:39], v[172:175], v[76:79]
	v_mfma_f32_16x16x32_bf16 v[72:75], v[44:47], v[172:175], v[72:75]
	v_mfma_f32_16x16x32_bf16 v[28:31], v[36:39], v[180:183], v[28:31]
	v_mfma_f32_16x16x32_bf16 v[24:27], v[44:47], v[180:183], v[24:27]
	v_mfma_f32_16x16x32_bf16 v[12:15], v[36:39], v[188:191], v[12:15]
	v_mfma_f32_16x16x32_bf16 v[8:11], v[44:47], v[188:191], v[8:11]
	s_setprio 0
	s_setprio 1
	v_mfma_f32_16x16x32_bf16 v[20:23], v[48:51], v[176:179], 0
	v_mfma_f32_16x16x32_bf16 v[16:19], v[64:67], v[176:179], 0
	v_mfma_f32_16x16x32_bf16 v[4:7], v[48:51], v[184:187], 0
	v_mfma_f32_16x16x32_bf16 v[0:3], v[64:67], v[184:187], 0
	v_mfma_f32_16x16x32_bf16 v[32:35], v[48:51], v[160:163], 0
	v_mfma_f32_16x16x32_bf16 v[36:39], v[64:67], v[160:163], 0
	v_mfma_f32_16x16x32_bf16 v[40:43], v[48:51], v[168:171], 0
	v_mfma_f32_16x16x32_bf16 v[44:47], v[64:67], v[168:171], 0
	v_mfma_f32_16x16x32_bf16 v[20:23], v[56:59], v[180:183], v[20:23]
	v_mfma_f32_16x16x32_bf16 v[16:19], v[68:71], v[180:183], v[16:19]
	v_mfma_f32_16x16x32_bf16 v[4:7], v[56:59], v[188:191], v[4:7]
	v_mfma_f32_16x16x32_bf16 v[0:3], v[68:71], v[188:191], v[0:3]
	v_mfma_f32_16x16x32_bf16 v[32:35], v[56:59], v[164:167], v[32:35]
	v_mfma_f32_16x16x32_bf16 v[36:39], v[68:71], v[164:167], v[36:39]
	v_mfma_f32_16x16x32_bf16 v[40:43], v[56:59], v[172:175], v[40:43]
	v_mfma_f32_16x16x32_bf16 v[44:47], v[68:71], v[172:175], v[44:47]
	s_setprio 0
	s_barrier
	s_add_i32 s69, 0, 0x18000
	s_add_i32 s70, 0, 0x1c000
	v_add_u32_e32 v60, s69, v231
	v_add_u32_e32 v80, s70, v231
	ds_read_b128 v[48:51], v60
	ds_read_b128 v[52:55], v60 offset:1024
	ds_read_b128 v[56:59], v60 offset:2048
	ds_read_b128 v[60:63], v60 offset:3072
	ds_read_b128 v[64:67], v80
	ds_read_b128 v[68:71], v80 offset:1024
	ds_read_b128 v[160:163], v80 offset:2048
	ds_read_b128 v[164:167], v80 offset:3072
	s_add_u32 s44, s44, 0x40000
	s_addc_u32 s45, s45, 0
	s_mov_b32 m0, s54
	v_lshl_add_u64 v[218:219], s[44:45], 0, v[194:195]
	ds_read_b128 v[80:83], v234 offset:32768
	ds_read_b128 v[84:87], v234 offset:33792
	ds_read_b128 v[168:171], v234 offset:34816
	ds_read_b128 v[172:175], v234 offset:35840
	ds_read_b128 v[176:179], v234 offset:36864
	ds_read_b128 v[180:183], v234 offset:37888
	ds_read_b128 v[184:187], v234 offset:38912
	ds_read_b128 v[188:191], v234 offset:39936
	global_load_lds_dwordx4 v[218:219], off
	v_lshl_add_u64 v[218:219], s[44:45], 0, v[198:199]
	s_mov_b32 m0, s55
	s_nop 0
	global_load_lds_dwordx4 v[218:219], off
	s_waitcnt vmcnt(8)
	s_waitcnt lgkmcnt(0)
	s_barrier
	s_setprio 1
	s_waitcnt lgkmcnt(0)
	v_mfma_f32_16x16x32_bf16 v[156:159], v[48:51], v[80:83], v[156:159]
	v_mfma_f32_16x16x32_bf16 v[152:155], v[56:59], v[80:83], v[152:155]
	v_mfma_f32_16x16x32_bf16 v[140:143], v[48:51], v[168:171], v[140:143]
	v_mfma_f32_16x16x32_bf16 v[136:139], v[56:59], v[168:171], v[136:139]
	v_mfma_f32_16x16x32_bf16 v[124:127], v[48:51], v[176:179], v[124:127]
	v_mfma_f32_16x16x32_bf16 v[120:123], v[56:59], v[176:179], v[120:123]
	v_mfma_f32_16x16x32_bf16 v[108:111], v[48:51], v[184:187], v[108:111]
	v_mfma_f32_16x16x32_bf16 v[104:107], v[56:59], v[184:187], v[104:107]
	v_mfma_f32_16x16x32_bf16 v[156:159], v[52:55], v[84:87], v[156:159]
	v_mfma_f32_16x16x32_bf16 v[152:155], v[60:63], v[84:87], v[152:155]
	v_mfma_f32_16x16x32_bf16 v[140:143], v[52:55], v[172:175], v[140:143]
	v_mfma_f32_16x16x32_bf16 v[136:139], v[60:63], v[172:175], v[136:139]
	v_mfma_f32_16x16x32_bf16 v[124:127], v[52:55], v[180:183], v[124:127]
	v_mfma_f32_16x16x32_bf16 v[120:123], v[60:63], v[180:183], v[120:123]
	v_mfma_f32_16x16x32_bf16 v[108:111], v[52:55], v[188:191], v[108:111]
	v_mfma_f32_16x16x32_bf16 v[104:107], v[60:63], v[188:191], v[104:107]
	s_setprio 0
	s_setprio 1
	v_mfma_f32_16x16x32_bf16 v[148:151], v[64:67], v[80:83], v[148:151]
	v_mfma_f32_16x16x32_bf16 v[80:83], v[160:163], v[80:83], v[144:147]
	v_mfma_f32_16x16x32_bf16 v[144:147], v[164:167], v[84:87], v[80:83]
	v_mfma_f32_16x16x32_bf16 v[80:83], v[64:67], v[168:171], v[132:135]
	v_mfma_f32_16x16x32_bf16 v[132:135], v[68:71], v[172:175], v[80:83]
	v_mfma_f32_16x16x32_bf16 v[80:83], v[160:163], v[168:171], v[128:131]
	v_mfma_f32_16x16x32_bf16 v[128:131], v[164:167], v[172:175], v[80:83]
	v_mfma_f32_16x16x32_bf16 v[80:83], v[64:67], v[176:179], v[116:119]
	v_mfma_f32_16x16x32_bf16 v[116:119], v[68:71], v[180:183], v[80:83]
	v_mfma_f32_16x16x32_bf16 v[80:83], v[160:163], v[176:179], v[112:115]
	v_mfma_f32_16x16x32_bf16 v[112:115], v[164:167], v[180:183], v[80:83]
	v_mfma_f32_16x16x32_bf16 v[80:83], v[64:67], v[184:187], v[100:103]
	v_mfma_f32_16x16x32_bf16 v[100:103], v[68:71], v[188:191], v[80:83]
	v_mfma_f32_16x16x32_bf16 v[80:83], v[160:163], v[184:187], v[96:99]
	v_mfma_f32_16x16x32_bf16 v[148:151], v[68:71], v[84:87], v[148:151]
	v_mfma_f32_16x16x32_bf16 v[96:99], v[164:167], v[188:191], v[80:83]
	s_setprio 0
	s_barrier
	s_add_i32 s44, s69, s49
	v_lshl_add_u64 v[84:85], v[222:223], 0, s[24:25]
	s_mov_b32 m0, s44
	s_nop 0
	ds_read_b128 v[80:83], v234 offset:49152
	ds_read_b128 v[168:171], v234 offset:50176
	ds_read_b128 v[172:175], v234 offset:51200
	ds_read_b128 v[176:179], v234 offset:52224
	ds_read_b128 v[180:183], v234 offset:53248
	ds_read_b128 v[184:187], v234 offset:54272
	ds_read_b128 v[188:191], v234 offset:55296
	ds_read_b128 v[218:221], v234 offset:56320
	global_load_lds_dwordx4 v[84:85], off
	s_add_i32 m0, s44, 0x2000
	s_add_u32 s12, s12, 0x40080
	v_lshl_add_u64 v[84:85], v[224:225], 0, s[24:25]
	s_addc_u32 s13, s13, 0
	s_add_i32 s44, s70, s49
	global_load_lds_dwordx4 v[84:85], off
	v_lshl_add_u64 v[84:85], s[12:13], 0, v[196:197]
	s_mov_b32 m0, s44
	s_nop 0
	global_load_lds_dwordx4 v[84:85], off
	v_lshl_add_u64 v[84:85], s[12:13], 0, v[200:201]
	s_add_i32 m0, s44, 0x2000
	s_nop 0
	global_load_lds_dwordx4 v[84:85], off
	v_lshl_add_u64 v[84:85], v[240:241], 0, s[24:25]
	s_mov_b32 m0, s58
	s_nop 0
	global_load_lds_dwordx4 v[84:85], off
	v_lshl_add_u64 v[84:85], v[242:243], 0, s[24:25]
	s_mov_b32 m0, s59
	s_nop 0
	global_load_lds_dwordx4 v[84:85], off
	s_waitcnt vmcnt(8)
	s_waitcnt lgkmcnt(0)
	s_barrier
	s_setprio 1
	s_waitcnt lgkmcnt(0)
	v_mfma_f32_16x16x32_bf16 v[84:87], v[48:51], v[80:83], v[92:95]
	v_mfma_f32_16x16x32_bf16 v[92:95], v[52:55], v[168:171], v[84:87]
	v_mfma_f32_16x16x32_bf16 v[84:87], v[56:59], v[80:83], v[88:91]
	v_mfma_f32_16x16x32_bf16 v[76:79], v[48:51], v[172:175], v[76:79]
	v_mfma_f32_16x16x32_bf16 v[72:75], v[56:59], v[172:175], v[72:75]
	v_mfma_f32_16x16x32_bf16 v[28:31], v[48:51], v[180:183], v[28:31]
	v_mfma_f32_16x16x32_bf16 v[24:27], v[56:59], v[180:183], v[24:27]
	v_mfma_f32_16x16x32_bf16 v[12:15], v[48:51], v[188:191], v[12:15]
	v_mfma_f32_16x16x32_bf16 v[8:11], v[56:59], v[188:191], v[8:11]
	v_mfma_f32_16x16x32_bf16 v[88:91], v[60:63], v[168:171], v[84:87]
	v_mfma_f32_16x16x32_bf16 v[76:79], v[52:55], v[176:179], v[76:79]
	v_mfma_f32_16x16x32_bf16 v[72:75], v[60:63], v[176:179], v[72:75]
	v_mfma_f32_16x16x32_bf16 v[28:31], v[52:55], v[184:187], v[28:31]
	v_mfma_f32_16x16x32_bf16 v[24:27], v[60:63], v[184:187], v[24:27]
	v_mfma_f32_16x16x32_bf16 v[12:15], v[52:55], v[218:221], v[12:15]
	v_mfma_f32_16x16x32_bf16 v[8:11], v[60:63], v[218:221], v[8:11]
	s_setprio 0
	s_setprio 1
	v_mfma_f32_16x16x32_bf16 v[32:35], v[64:67], v[80:83], v[32:35]
	v_mfma_f32_16x16x32_bf16 v[84:87], v[68:71], v[168:171], v[32:35]
	v_mfma_f32_16x16x32_bf16 v[32:35], v[160:163], v[80:83], v[36:39]
	v_mfma_f32_16x16x32_bf16 v[80:83], v[164:167], v[168:171], v[32:35]
	v_mfma_f32_16x16x32_bf16 v[32:35], v[64:67], v[172:175], v[40:43]
	v_mfma_f32_16x16x32_bf16 v[60:63], v[68:71], v[176:179], v[32:35]
	v_mfma_f32_16x16x32_bf16 v[32:35], v[160:163], v[172:175], v[44:47]
	v_mfma_f32_16x16x32_bf16 v[20:23], v[64:67], v[180:183], v[20:23]
	v_mfma_f32_16x16x32_bf16 v[16:19], v[160:163], v[180:183], v[16:19]
	v_mfma_f32_16x16x32_bf16 v[4:7], v[64:67], v[188:191], v[4:7]
	v_mfma_f32_16x16x32_bf16 v[0:3], v[160:163], v[188:191], v[0:3]
	v_mfma_f32_16x16x32_bf16 v[52:55], v[164:167], v[176:179], v[32:35]
	v_mfma_f32_16x16x32_bf16 v[20:23], v[68:71], v[184:187], v[20:23]
	v_mfma_f32_16x16x32_bf16 v[16:19], v[164:167], v[184:187], v[16:19]
	v_mfma_f32_16x16x32_bf16 v[4:7], v[68:71], v[218:221], v[4:7]
	v_mfma_f32_16x16x32_bf16 v[0:3], v[164:167], v[218:221], v[0:3]
	s_setprio 0
	s_barrier
	s_add_i32 s68, s68, 2
	s_add_u32 s10, s10, 0x100
	s_addc_u32 s11, s11, 0
	s_add_u32 s33, s33, 0x100
	s_addc_u32 s67, s67, 0
	s_cmp_gt_u32 s68, 13

.LBB0_993:
	s_mov_b32 s69, s41
	s_add_i32 s41, s41, 1
	s_cmp_lt_u32 s69, 3
	s_mov_b64 s[0:1], s[18:19]
	s_cselect_b64 s[46:47], -1, 0
	s_add_i32 s18, s41, s52
	s_mov_b64 s[4:5], s[16:17]
	s_and_b64 s[16:17], s[46:47], exec
	s_mov_b32 s71, s42
	s_cselect_b32 s42, s40, s42
	s_mov_b32 s70, s36
	s_cselect_b32 s36, s18, s36
	s_ashr_i32 s43, s42, 31
	s_lshl_b64 s[16:17], s[42:43], 19
	s_add_u32 s18, s6, s16
	s_addc_u32 s19, s7, s17
	s_and_b64 s[16:17], s[46:47], exec
	s_cselect_b32 s43, s19, s1
	s_cselect_b32 s72, s18, s0
	s_ashr_i32 s37, s36, 31
	s_lshl_b64 s[16:17], s[36:37], 19
	s_add_u32 s16, s55, s16
	s_addc_u32 s17, s56, s17
	s_and_b64 s[46:47], s[46:47], exec
	s_cselect_b32 s37, s17, s5
	s_cselect_b32 s73, s16, s4
	s_add_u32 s0, s0, 0x40080
	s_addc_u32 s1, s1, 0
	s_add_u32 s74, s4, 0x100
	s_addc_u32 s75, s5, 0
	s_mov_b32 s76, -2
	ds_read_b128 v[128:131], v144
	ds_read_b128 v[132:135], v144 offset:1024
	ds_read_b128 v[164:167], v144 offset:2048
	ds_read_b128 v[168:171], v144 offset:3072
	ds_read_b128 v[172:175], v145
	ds_read_b128 v[176:179], v145 offset:1024
	ds_read_b128 v[194:197], v145 offset:2048
	ds_read_b128 v[198:201], v145 offset:3072
	s_add_u32 s4, s0, 0xfffc0080
	s_addc_u32 s5, s1, -1
	s_cmp_eq_u32 s76, 12
	s_cselect_b32 s47, s43, s5
	s_cselect_b32 s46, s72, s4
	s_cselect_b32 s5, s37, s75
	s_cselect_b32 s4, s73, s74
	v_lshl_add_u64 v[136:137], s[0:1], 0, v[160:161]
	s_add_i32 m0, s58, 0xc000
	ds_read_b128 v[202:205], v146
	ds_read_b128 v[206:209], v146 offset:1024
	ds_read_b128 v[210:213], v146 offset:2048
	ds_read_b128 v[214:217], v146 offset:3072
	ds_read_b128 v[218:221], v146 offset:4096
	ds_read_b128 v[222:225], v146 offset:5120
	ds_read_b128 v[228:231], v146 offset:6144
	ds_read_b128 v[232:235], v146 offset:7168
	global_load_lds_dwordx4 v[136:137], off
	v_lshl_add_u64 v[136:137], s[0:1], 0, v[162:163]
	s_add_i32 m0, s58, 0xe000
	s_nop 0
	global_load_lds_dwordx4 v[136:137], off
	s_waitcnt vmcnt(8)
	s_waitcnt lgkmcnt(0)
	s_barrier
	s_setprio 1
	s_waitcnt lgkmcnt(0)
	v_mfma_f32_16x16x32_bf16 v[124:127], v[128:131], v[202:205], 0
	v_mfma_f32_16x16x32_bf16 v[120:123], v[164:167], v[202:205], 0
	v_mfma_f32_16x16x32_bf16 v[108:111], v[128:131], v[210:213], 0
	v_mfma_f32_16x16x32_bf16 v[104:107], v[164:167], v[210:213], 0
	v_mfma_f32_16x16x32_bf16 v[92:95], v[128:131], v[218:221], 0
	v_mfma_f32_16x16x32_bf16 v[88:91], v[164:167], v[218:221], 0
	v_mfma_f32_16x16x32_bf16 v[76:79], v[128:131], v[228:231], 0
	v_mfma_f32_16x16x32_bf16 v[72:75], v[164:167], v[228:231], 0
	v_mfma_f32_16x16x32_bf16 v[124:127], v[132:135], v[206:209], v[124:127]
	v_mfma_f32_16x16x32_bf16 v[120:123], v[168:171], v[206:209], v[120:123]
	v_mfma_f32_16x16x32_bf16 v[108:111], v[132:135], v[214:217], v[108:111]
	v_mfma_f32_16x16x32_bf16 v[104:107], v[168:171], v[214:217], v[104:107]
	v_mfma_f32_16x16x32_bf16 v[92:95], v[132:135], v[222:225], v[92:95]
	v_mfma_f32_16x16x32_bf16 v[88:91], v[168:171], v[222:225], v[88:91]
	v_mfma_f32_16x16x32_bf16 v[76:79], v[132:135], v[232:235], v[76:79]
	v_mfma_f32_16x16x32_bf16 v[72:75], v[168:171], v[232:235], v[72:75]
	s_setprio 0
	s_setprio 1
	v_mfma_f32_16x16x32_bf16 v[116:119], v[172:175], v[202:205], 0
	v_mfma_f32_16x16x32_bf16 v[112:115], v[194:197], v[202:205], 0
	v_mfma_f32_16x16x32_bf16 v[100:103], v[172:175], v[210:213], 0
	v_mfma_f32_16x16x32_bf16 v[96:99], v[194:197], v[210:213], 0
	v_mfma_f32_16x16x32_bf16 v[84:87], v[172:175], v[218:221], 0
	v_mfma_f32_16x16x32_bf16 v[80:83], v[194:197], v[218:221], 0
	v_mfma_f32_16x16x32_bf16 v[68:71], v[172:175], v[228:231], 0
	v_mfma_f32_16x16x32_bf16 v[64:67], v[194:197], v[228:231], 0
	v_mfma_f32_16x16x32_bf16 v[116:119], v[176:179], v[206:209], v[116:119]
	v_mfma_f32_16x16x32_bf16 v[112:115], v[198:201], v[206:209], v[112:115]
	v_mfma_f32_16x16x32_bf16 v[100:103], v[176:179], v[214:217], v[100:103]
	v_mfma_f32_16x16x32_bf16 v[96:99], v[198:201], v[214:217], v[96:99]
	v_mfma_f32_16x16x32_bf16 v[84:87], v[176:179], v[222:225], v[84:87]
	v_mfma_f32_16x16x32_bf16 v[80:83], v[198:201], v[222:225], v[80:83]
	v_mfma_f32_16x16x32_bf16 v[68:71], v[176:179], v[232:235], v[68:71]
	v_mfma_f32_16x16x32_bf16 v[64:67], v[198:201], v[232:235], v[64:67]
	s_setprio 0
	s_barrier
	s_add_i32 s77, s48, s57
	v_lshl_add_u64 v[136:137], s[4:5], 0, v[156:157]
	s_mov_b32 m0, s77
	ds_read_b128 v[202:205], v146 offset:16384
	ds_read_b128 v[206:209], v146 offset:17408
	ds_read_b128 v[210:213], v146 offset:18432
	ds_read_b128 v[214:217], v146 offset:19456
	ds_read_b128 v[218:221], v146 offset:20480
	ds_read_b128 v[222:225], v146 offset:21504
	ds_read_b128 v[228:231], v146 offset:22528
	ds_read_b128 v[232:235], v146 offset:23552
	global_load_lds_dwordx4 v[136:137], off
	s_add_i32 m0, s77, 0x2000
	s_add_u32 s78, s4, 0x40000
	v_lshl_add_u64 v[150:151], s[4:5], 0, v[152:153]
	s_addc_u32 s79, s5, 0
	s_add_i32 s77, s49, s57
	global_load_lds_dwordx4 v[150:151], off
	v_lshl_add_u64 v[180:181], s[78:79], 0, v[156:157]
	s_mov_b32 m0, s77
	v_lshl_add_u64 v[236:237], s[46:47], 0, v[154:155]
	global_load_lds_dwordx4 v[180:181], off
	v_lshl_add_u64 v[180:181], s[78:79], 0, v[152:153]
	s_add_i32 m0, s77, 0x2000
	s_nop 0
	global_load_lds_dwordx4 v[180:181], off
	v_lshl_add_u64 v[180:181], s[46:47], 0, v[158:159]
	s_mov_b32 m0, s58
	s_nop 0
	global_load_lds_dwordx4 v[180:181], off
	s_mov_b32 m0, s59
	s_nop 0
	global_load_lds_dwordx4 v[236:237], off
	s_waitcnt vmcnt(8)
	s_waitcnt lgkmcnt(0)
	s_barrier
	s_setprio 1
	s_waitcnt lgkmcnt(0)
	v_mfma_f32_16x16x32_bf16 v[60:63], v[128:131], v[202:205], 0
	v_mfma_f32_16x16x32_bf16 v[56:59], v[164:167], v[202:205], 0
	v_mfma_f32_16x16x32_bf16 v[44:47], v[128:131], v[210:213], 0
	v_mfma_f32_16x16x32_bf16 v[40:43], v[164:167], v[210:213], 0
	v_mfma_f32_16x16x32_bf16 v[28:31], v[128:131], v[218:221], 0
	v_mfma_f32_16x16x32_bf16 v[24:27], v[164:167], v[218:221], 0
	v_mfma_f32_16x16x32_bf16 v[12:15], v[128:131], v[228:231], 0
	v_mfma_f32_16x16x32_bf16 v[8:11], v[164:167], v[228:231], 0
	v_mfma_f32_16x16x32_bf16 v[60:63], v[132:135], v[206:209], v[60:63]
	v_mfma_f32_16x16x32_bf16 v[56:59], v[168:171], v[206:209], v[56:59]
	v_mfma_f32_16x16x32_bf16 v[44:47], v[132:135], v[214:217], v[44:47]
	v_mfma_f32_16x16x32_bf16 v[40:43], v[168:171], v[214:217], v[40:43]
	v_mfma_f32_16x16x32_bf16 v[28:31], v[132:135], v[222:225], v[28:31]
	v_mfma_f32_16x16x32_bf16 v[24:27], v[168:171], v[222:225], v[24:27]
	v_mfma_f32_16x16x32_bf16 v[12:15], v[132:135], v[232:235], v[12:15]
	v_mfma_f32_16x16x32_bf16 v[8:11], v[168:171], v[232:235], v[8:11]
	s_setprio 0
	s_setprio 1
	v_mfma_f32_16x16x32_bf16 v[52:55], v[172:175], v[202:205], 0
	v_mfma_f32_16x16x32_bf16 v[48:51], v[194:197], v[202:205], 0
	v_mfma_f32_16x16x32_bf16 v[36:39], v[172:175], v[210:213], 0
	v_mfma_f32_16x16x32_bf16 v[32:35], v[194:197], v[210:213], 0
	v_mfma_f32_16x16x32_bf16 v[20:23], v[172:175], v[218:221], 0
	v_mfma_f32_16x16x32_bf16 v[16:19], v[194:197], v[218:221], 0
	v_mfma_f32_16x16x32_bf16 v[4:7], v[172:175], v[228:231], 0
	v_mfma_f32_16x16x32_bf16 v[0:3], v[194:197], v[228:231], 0
	v_mfma_f32_16x16x32_bf16 v[52:55], v[176:179], v[206:209], v[52:55]
	v_mfma_f32_16x16x32_bf16 v[48:51], v[198:201], v[206:209], v[48:51]
	v_mfma_f32_16x16x32_bf16 v[36:39], v[176:179], v[214:217], v[36:39]
	v_mfma_f32_16x16x32_bf16 v[32:35], v[198:201], v[214:217], v[32:35]
	v_mfma_f32_16x16x32_bf16 v[20:23], v[176:179], v[222:225], v[20:23]
	v_mfma_f32_16x16x32_bf16 v[16:19], v[198:201], v[222:225], v[16:19]
	v_mfma_f32_16x16x32_bf16 v[4:7], v[176:179], v[232:235], v[4:7]
	v_mfma_f32_16x16x32_bf16 v[0:3], v[198:201], v[232:235], v[0:3]
	s_setprio 0
	s_barrier
	v_add_u32_e32 v149, s51, v142
	ds_read_b128 v[128:131], v149
	ds_read_b128 v[132:135], v149 offset:1024
	ds_read_b128 v[164:167], v149 offset:2048
	ds_read_b128 v[168:171], v149 offset:3072
	v_add_u32_e32 v149, s53, v142
	ds_read_b128 v[172:175], v149
	ds_read_b128 v[176:179], v149 offset:1024
	ds_read_b128 v[194:197], v149 offset:2048
	ds_read_b128 v[198:201], v149 offset:3072
	s_add_u32 s46, s46, 0x40000
	s_addc_u32 s47, s47, 0
	s_mov_b32 m0, s60
	v_lshl_add_u64 v[238:239], s[46:47], 0, v[158:159]
	ds_read_b128 v[202:205], v146 offset:32768
	ds_read_b128 v[206:209], v146 offset:33792
	ds_read_b128 v[210:213], v146 offset:34816
	ds_read_b128 v[214:217], v146 offset:35840
	ds_read_b128 v[218:221], v146 offset:36864
	ds_read_b128 v[222:225], v146 offset:37888
	ds_read_b128 v[228:231], v146 offset:38912
	ds_read_b128 v[232:235], v146 offset:39936
	global_load_lds_dwordx4 v[238:239], off
	v_lshl_add_u64 v[238:239], s[46:47], 0, v[154:155]
	s_mov_b32 m0, s61
	s_nop 0
	global_load_lds_dwordx4 v[238:239], off
	s_waitcnt vmcnt(8)
	s_waitcnt lgkmcnt(0)
	s_barrier
	s_setprio 1
	s_waitcnt lgkmcnt(0)
	v_mfma_f32_16x16x32_bf16 v[124:127], v[128:131], v[202:205], v[124:127]
	v_mfma_f32_16x16x32_bf16 v[120:123], v[164:167], v[202:205], v[120:123]
	v_mfma_f32_16x16x32_bf16 v[108:111], v[128:131], v[210:213], v[108:111]
	v_mfma_f32_16x16x32_bf16 v[104:107], v[164:167], v[210:213], v[104:107]
	v_mfma_f32_16x16x32_bf16 v[92:95], v[128:131], v[218:221], v[92:95]
	v_mfma_f32_16x16x32_bf16 v[88:91], v[164:167], v[218:221], v[88:91]
	v_mfma_f32_16x16x32_bf16 v[76:79], v[128:131], v[228:231], v[76:79]
	v_mfma_f32_16x16x32_bf16 v[72:75], v[164:167], v[228:231], v[72:75]
	v_mfma_f32_16x16x32_bf16 v[124:127], v[132:135], v[206:209], v[124:127]
	v_mfma_f32_16x16x32_bf16 v[120:123], v[168:171], v[206:209], v[120:123]
	v_mfma_f32_16x16x32_bf16 v[108:111], v[132:135], v[214:217], v[108:111]
	v_mfma_f32_16x16x32_bf16 v[104:107], v[168:171], v[214:217], v[104:107]
	v_mfma_f32_16x16x32_bf16 v[92:95], v[132:135], v[222:225], v[92:95]
	v_mfma_f32_16x16x32_bf16 v[88:91], v[168:171], v[222:225], v[88:91]
	v_mfma_f32_16x16x32_bf16 v[76:79], v[132:135], v[232:235], v[76:79]
	v_mfma_f32_16x16x32_bf16 v[72:75], v[168:171], v[232:235], v[72:75]
	s_setprio 0
	s_setprio 1
	v_mfma_f32_16x16x32_bf16 v[116:119], v[172:175], v[202:205], v[116:119]
	v_mfma_f32_16x16x32_bf16 v[112:115], v[194:197], v[202:205], v[112:115]
	v_mfma_f32_16x16x32_bf16 v[100:103], v[172:175], v[210:213], v[100:103]
	v_mfma_f32_16x16x32_bf16 v[96:99], v[194:197], v[210:213], v[96:99]
	v_mfma_f32_16x16x32_bf16 v[84:87], v[172:175], v[218:221], v[84:87]
	v_mfma_f32_16x16x32_bf16 v[80:83], v[194:197], v[218:221], v[80:83]
	v_mfma_f32_16x16x32_bf16 v[68:71], v[172:175], v[228:231], v[68:71]
	v_mfma_f32_16x16x32_bf16 v[64:67], v[194:197], v[228:231], v[64:67]
	v_mfma_f32_16x16x32_bf16 v[116:119], v[176:179], v[206:209], v[116:119]
	v_mfma_f32_16x16x32_bf16 v[112:115], v[198:201], v[206:209], v[112:115]
	v_mfma_f32_16x16x32_bf16 v[100:103], v[176:179], v[214:217], v[100:103]
	v_mfma_f32_16x16x32_bf16 v[96:99], v[198:201], v[214:217], v[96:99]
	v_mfma_f32_16x16x32_bf16 v[84:87], v[176:179], v[222:225], v[84:87]
	v_mfma_f32_16x16x32_bf16 v[80:83], v[198:201], v[222:225], v[80:83]
	v_mfma_f32_16x16x32_bf16 v[68:71], v[176:179], v[232:235], v[68:71]
	v_mfma_f32_16x16x32_bf16 v[64:67], v[198:201], v[232:235], v[64:67]
	s_setprio 0
	s_barrier
	s_add_i32 s46, s51, s57
	v_lshl_add_u64 v[136:137], v[136:137], 0, s[22:23]
	s_mov_b32 m0, s46
	ds_read_b128 v[202:205], v146 offset:49152
	ds_read_b128 v[206:209], v146 offset:50176
	ds_read_b128 v[210:213], v146 offset:51200
	ds_read_b128 v[214:217], v146 offset:52224
	ds_read_b128 v[218:221], v146 offset:53248
	ds_read_b128 v[222:225], v146 offset:54272
	ds_read_b128 v[228:231], v146 offset:55296
	ds_read_b128 v[232:235], v146 offset:56320
	global_load_lds_dwordx4 v[136:137], off
	s_add_i32 m0, s46, 0x2000
	s_add_u32 s4, s4, 0x40080
	v_lshl_add_u64 v[136:137], v[150:151], 0, s[22:23]
	s_addc_u32 s5, s5, 0
	s_add_i32 s46, s53, s57
	global_load_lds_dwordx4 v[136:137], off
	v_lshl_add_u64 v[136:137], s[4:5], 0, v[156:157]
	s_mov_b32 m0, s46
	s_nop 0
	global_load_lds_dwordx4 v[136:137], off
	v_lshl_add_u64 v[136:137], s[4:5], 0, v[152:153]
	s_add_i32 m0, s46, 0x2000
	s_nop 0
	global_load_lds_dwordx4 v[136:137], off
	v_lshl_add_u64 v[136:137], v[180:181], 0, s[22:23]
	s_mov_b32 m0, s62
	s_nop 0
	global_load_lds_dwordx4 v[136:137], off
	v_lshl_add_u64 v[136:137], v[236:237], 0, s[22:23]
	s_mov_b32 m0, s63
	s_nop 0
	global_load_lds_dwordx4 v[136:137], off
	s_waitcnt vmcnt(8)
	s_waitcnt lgkmcnt(0)
	s_barrier
	s_setprio 1
	s_waitcnt lgkmcnt(0)
	v_mfma_f32_16x16x32_bf16 v[60:63], v[128:131], v[202:205], v[60:63]
	v_mfma_f32_16x16x32_bf16 v[56:59], v[164:167], v[202:205], v[56:59]
	v_mfma_f32_16x16x32_bf16 v[44:47], v[128:131], v[210:213], v[44:47]
	v_mfma_f32_16x16x32_bf16 v[40:43], v[164:167], v[210:213], v[40:43]
	v_mfma_f32_16x16x32_bf16 v[28:31], v[128:131], v[218:221], v[28:31]
	v_mfma_f32_16x16x32_bf16 v[24:27], v[164:167], v[218:221], v[24:27]
	v_mfma_f32_16x16x32_bf16 v[12:15], v[128:131], v[228:231], v[12:15]
	v_mfma_f32_16x16x32_bf16 v[8:11], v[164:167], v[228:231], v[8:11]
	v_mfma_f32_16x16x32_bf16 v[60:63], v[132:135], v[206:209], v[60:63]
	v_mfma_f32_16x16x32_bf16 v[56:59], v[168:171], v[206:209], v[56:59]
	v_mfma_f32_16x16x32_bf16 v[44:47], v[132:135], v[214:217], v[44:47]
	v_mfma_f32_16x16x32_bf16 v[40:43], v[168:171], v[214:217], v[40:43]
	v_mfma_f32_16x16x32_bf16 v[28:31], v[132:135], v[222:225], v[28:31]
	v_mfma_f32_16x16x32_bf16 v[24:27], v[168:171], v[222:225], v[24:27]
	v_mfma_f32_16x16x32_bf16 v[12:15], v[132:135], v[232:235], v[12:15]
	v_mfma_f32_16x16x32_bf16 v[8:11], v[168:171], v[232:235], v[8:11]
	s_setprio 0
	s_setprio 1
	v_mfma_f32_16x16x32_bf16 v[52:55], v[172:175], v[202:205], v[52:55]
	v_mfma_f32_16x16x32_bf16 v[48:51], v[194:197], v[202:205], v[48:51]
	v_mfma_f32_16x16x32_bf16 v[36:39], v[172:175], v[210:213], v[36:39]
	v_mfma_f32_16x16x32_bf16 v[32:35], v[194:197], v[210:213], v[32:35]
	v_mfma_f32_16x16x32_bf16 v[20:23], v[172:175], v[218:221], v[20:23]
	v_mfma_f32_16x16x32_bf16 v[16:19], v[194:197], v[218:221], v[16:19]
	v_mfma_f32_16x16x32_bf16 v[4:7], v[172:175], v[228:231], v[4:7]
	v_mfma_f32_16x16x32_bf16 v[0:3], v[194:197], v[228:231], v[0:3]
	v_mfma_f32_16x16x32_bf16 v[52:55], v[176:179], v[206:209], v[52:55]
	v_mfma_f32_16x16x32_bf16 v[48:51], v[198:201], v[206:209], v[48:51]
	v_mfma_f32_16x16x32_bf16 v[36:39], v[176:179], v[214:217], v[36:39]
	v_mfma_f32_16x16x32_bf16 v[32:35], v[198:201], v[214:217], v[32:35]
	v_mfma_f32_16x16x32_bf16 v[20:23], v[176:179], v[222:225], v[20:23]
	v_mfma_f32_16x16x32_bf16 v[16:19], v[198:201], v[222:225], v[16:19]
	v_mfma_f32_16x16x32_bf16 v[4:7], v[176:179], v[232:235], v[4:7]
	v_mfma_f32_16x16x32_bf16 v[0:3], v[198:201], v[232:235], v[0:3]
	s_setprio 0
	s_barrier
	s_add_i32 s76, s76, 2
	s_add_u32 s0, s0, 0x100
	s_addc_u32 s1, s1, 0
	s_add_u32 s74, s74, 0x100
	s_addc_u32 s75, s75, 0
	s_cmp_gt_u32 s76, 13
